# DSA attention units handed out from per-XCD sub-lists (head = XCD) so a head's K/V stream is shared through one L2
# speedup vs baseline: 1.0053x; 1.0053x over previous
.LBB0_805:
	s_and_b64 vcc, exec, s[4:5]
	s_cbranch_vccz .LBB0_816
	s_cmp_lg_u32 s28, 0
	s_cbranch_scc1 .Ldq0_wait
	s_getreg_b32 s0, hwreg(HW_REG_XCC_ID, 0, 4)
	s_and_b32 s0, s0, 7
	s_mov_b32 s1, 0
	v_cmp_eq_u32_e32 vcc, 0, v204
	s_and_saveexec_b64 s[4:5], vcc
	s_cbranch_execz .Ldq0_done
.Ldq0_try:
	s_add_u32 s2, s0, s1
	s_and_b32 s2, s2, 7
	s_lshl_b32 s3, s2, 8
	s_add_u32 s3, s3, 0xd000
	v_mov_b32_e32 v2, s3
	v_mov_b32_e32 v3, 1
	s_nop 0
	global_atomic_add v3, v2, v3, s[90:91] sc0
	s_waitcnt vmcnt(0)
	v_readfirstlane_b32 s3, v3
	s_cmp_lt_u32 s3, 32
	s_cbranch_scc1 .Ldq0_got
	s_add_u32 s1, s1, 1
	s_cmp_lt_u32 s1, 8
	s_cbranch_scc1 .Ldq0_try
	s_mov_b32 s2, 0
	s_mov_b32 s3, 0
.Ldq0_got:
	s_lshl_b32 s3, s3, 3
	s_add_u32 s3, s3, s2
	s_addk_i32 s3, 0x540
	v_mov_b32_e32 v2, s3
	ds_write_b32 v207, v2 offset:4
	s_waitcnt lgkmcnt(0)
.Ldq0_done:
	s_mov_b64 exec, s[4:5]
.Ldq0_wait:
	s_barrier
	ds_read_b32 v2, v207 offset:4
	s_waitcnt lgkmcnt(0)
	v_readfirstlane_b32 s29, v2
	s_barrier
	s_add_i32 s0, s29, 0xfffffac0
	s_lshr_b32 s3, s0, 3
	s_sub_i32 s2, 31, s3
	s_cmp_lg_u32 s28, 0
	s_cbranch_scc1 .LBB0_939
	s_lshl_b32 s0, s2, 8
	s_add_u32 s0, s90, s0
	s_addc_u32 s1, s91, 0
	s_add_u32 s4, s0, 0x10000
	s_addc_u32 s5, s1, 0
	s_mov_b32 s0, 1
	s_branch .LBB0_809

.Ldq1_try:
	s_add_u32 s2, s0, s1
	s_and_b32 s2, s2, 7
	s_lshl_b32 s3, s2, 8
	s_add_u32 s3, s3, 0xd800
	v_mov_b32_e32 v2, s3
	v_mov_b32_e32 v3, 1
	s_nop 0
	global_atomic_add v3, v2, v3, s[90:91] sc0
	s_waitcnt vmcnt(0)
	v_readfirstlane_b32 s3, v3
	s_cmp_lt_u32 s3, 32
	s_cbranch_scc1 .Ldq1_got
	s_add_u32 s1, s1, 1
	s_cmp_lt_u32 s1, 8
	s_cbranch_scc1 .Ldq1_try
	s_mov_b32 s2, 0
	s_mov_b32 s3, 0

.Ldq1_wait:
	s_barrier
	ds_read_b32 v2, v207 offset:4
	s_waitcnt lgkmcnt(0)
	v_readfirstlane_b32 s29, v2
	s_barrier
	s_add_i32 s0, s29, 0xfffffac0
	s_lshr_b32 s3, s0, 3
	s_cmp_lg_u32 s28, 0
	s_cbranch_scc1 .LBB0_2560
	s_lshl_b32 s0, s3, 6
	s_sub_i32 s0, 0xfc0, s0
	s_lshl_b32 s0, s0, 2
	s_add_u32 s0, s90, s0
	s_addc_u32 s1, s91, 0
	s_add_u32 s4, s0, 0x10000
	s_addc_u32 s5, s1, 0
	s_mov_b32 s0, 1
	s_branch .LBB0_2430
